# attention tile loop in two stage-specialised bodies (stage in LDS immediates: no per-tile K/V address VALU)
# baseline (speedup 1.0000x reference)
.LBB0_254:
	s_cmp_lt_i32 s59, 1
	s_cbranch_scc1 .LBB0_360
	s_add_u32 s3, s66, 0x20200000
	v_writelane_b32 v254, s90, 11
	s_addc_u32 s6, s67, 0
	s_ashr_i32 s0, s88, 4
	v_writelane_b32 v254, s91, 12
	s_and_b32 s0, s0, -2
	v_writelane_b32 v254, s0, 13
	v_writelane_b32 v254, s88, 14
	s_and_b32 s0, s88, 31
	v_writelane_b32 v254, s0, 15
	s_and_b32 s0, s87, 0xffffffc0
	v_mov_b32_e32 v0, 0x3e4ccccd
	v_writelane_b32 v254, s0, 16
	s_lshl_b32 s0, s0, 2
	v_add_f32_e32 v0, s1, v0
	s_add_i32 s96, s0, 0
	s_add_i32 s0, s89, -4
	s_lshl_b32 s1, s89, 7
	s_lshl_b32 s4, s89, 18
	s_bfe_u32 s7, s87, 0x20006
	s_lshl_b32 s9, s0, 13
	s_and_b32 s1, s1, 0xffffff00
	s_and_b32 s4, s4, 0x40000
	s_lshl_b32 s0, s0, 13
	s_lshr_b32 s8, s87, 8
	s_lshl_b32 s14, s7, 5
	s_add_i32 s96, s96, 0x20200
	s_add_i32 s10, s1, s4
	s_lshl_b32 s11, s89, 13
	s_add_i32 s12, s0, 0x10000
	s_cmpk_lt_u32 s87, 0x100
	s_cselect_b64 s[0:1], -1, 0
	s_and_b64 s[4:5], s[0:1], exec
	s_movk_i32 s5, 0x400
	v_writelane_b32 v254, s89, 17
	s_cselect_b32 s4, s11, s12
	s_cselect_b32 s11, 0x8000, s5
	s_mov_b32 s5, 0x10000
	v_writelane_b32 v254, s87, 18
	s_cselect_b32 s12, s5, 0x800
	s_mov_b32 s5, 0x18000
	s_cselect_b32 s20, 0xc0, 0
	s_cselect_b32 s16, s5, 0xc00
	s_mov_b32 s5, 0x20000
	v_writelane_b32 v254, s20, 19
	s_cselect_b32 s20, 0x80, 0
	s_cselect_b32 s17, s5, 0x1000
	s_mov_b32 s5, 0x28000
	v_writelane_b32 v254, s20, 20
	s_cselect_b32 s20, 64, 0
	s_cselect_b32 s18, s5, 0x1400
	s_mov_b32 s5, 0x30000
	v_writelane_b32 v254, s20, 21
	s_cselect_b32 s19, s5, 0x1800
	s_mov_b32 s5, 0x38000
	s_cselect_b32 s63, s95, s6
	v_writelane_b32 v254, s94, 22
	s_cselect_b32 s5, s5, 0x1c00
	s_cselect_b32 s93, s10, s9
	v_writelane_b32 v254, s95, 23
	s_cselect_b32 s62, s94, s3
	s_add_i32 s97, s4, 0
	s_lshl_b32 s4, s8, 14
	v_writelane_b32 v254, s4, 24
	s_lshl_b32 s4, s7, 15
	s_add_i32 s75, s97, 0x400
	s_add_i32 s68, s97, 0x800
	s_add_i32 s69, s97, 0xc00
	s_add_i32 s78, s97, 0x1000
	s_add_i32 s79, s97, 0x1400
	s_add_i32 s54, s97, 0x1800
	s_add_i32 s55, s97, 0x1c00
	s_lshl_b32 s3, s8, 7
	s_add_i32 s71, s97, 0x10000
	s_add_i32 s92, s97, 0x10400
	s_add_i32 s70, s97, 0x10800
	s_add_i32 s80, s97, 0x10c00
	s_add_i32 s81, s97, 0x11000
	s_add_i32 s50, s97, 0x11400
	s_add_i32 s51, s97, 0x11800
	s_add_i32 s94, s97, 0x11c00
	s_add_i32 s95, s4, 0
	s_cmp_eq_u32 s8, 1
	s_cselect_b64 s[6:7], -1, 0
	v_writelane_b32 v254, s6, 25
	s_lshl_b32 s4, s8, 4
	s_mov_b32 s15, 0
	v_writelane_b32 v254, s7, 26
	v_writelane_b32 v254, s4, 27
	v_writelane_b32 v254, s14, 28
	s_add_i32 s4, s14, 0xffffffa5
	v_writelane_b32 v254, s4, 29
	v_writelane_b32 v254, s5, 30
	s_add_i32 s4, s93, s5
	v_writelane_b32 v254, s4, 31
	v_writelane_b32 v254, s16, 32
	s_add_i32 s4, s93, s16
	v_writelane_b32 v254, s4, 33
	v_writelane_b32 v254, s19, 34
	s_add_i32 s4, s93, s19
	v_writelane_b32 v254, s4, 35
	v_writelane_b32 v254, s12, 36
	s_add_i32 s4, s93, s12
	v_writelane_b32 v254, s4, 37
	v_writelane_b32 v254, s18, 38
	s_add_i32 s4, s93, s18
	v_writelane_b32 v254, s4, 39
	v_writelane_b32 v254, s11, 40
	s_add_i32 s4, s93, s11
	v_writelane_b32 v254, s4, 41
	v_writelane_b32 v254, s17, 42
	s_add_i32 s4, s93, s17
	v_xor_b32_e32 v210, 0x80000000, v0
	v_writelane_b32 v254, s4, 43
	s_lshl_b32 s14, s3, 1
	v_mov_b32_e32 v212, v210
	v_mov_b32_e32 v213, v210
	v_mov_b32_e32 v1, 0
	s_mov_b32 s74, 0x41000000
	v_mov_b32_e32 v214, 0x3727c5ac
	v_mov_b32_e32 v215, 0x41b17218
	v_mov_b32_e32 v216, 0xff800000
	v_writelane_b32 v254, s14, 44
	s_mov_b32 s72, s15
	s_nop 0
	v_writelane_b32 v254, s15, 45
	s_branch .LBB0_257

.Lat_entry:
	s_mov_b32 s92, m0
	s_add_i32 s71, s97, 0x8000
	s_movk_i32 s81, 0x7f
	s_mov_b32 s80, 0x20000
	s_cmp_lg_u64 s[0:1], 0
	s_mov_b32 s100, 0x8000
	s_cselect_b32 s100, 0x80000, s100
	s_add_i32 s51, s90, s100
	s_add_u32 s50, s62, s51
	s_addc_u32 s51, s63, 0
	s_mov_b32 s84, 1
	s_mov_b32 s94, 0xff800000
	v_mov_b32_e32 v246, 0
	v_mov_b32_e32 v247, 0
	v_mov_b32_e32 v248, 0
	v_mov_b32_e32 v249, 0
	v_mov_b32_e32 v250, 0
	v_mov_b32_e32 v251, 0
	v_mov_b32_e32 v252, 0
	v_mov_b32_e32 v253, 0
	v_readlane_b32 s4, v254, 24
	v_and_b32_e32 v234, 15, v211
	v_lshrrev_b32_e32 v235, 4, v211
	v_xor_b32_e32 v236, v234, v235
	v_lshlrev_b32_e32 v236, 4, v236
	v_lshl_add_u32 v236, v234, 8, v236
	v_add_u32_e32 v221, s4, v236
	v_lshlrev_b32_e32 v237, 2, v235
	v_sub_u32_e32 v237, v234, v237
	v_add_u32_e32 v223, s3, v237
	v_bfe_u32 v237, v211, 5, 1
	v_lshlrev_b32_e32 v237, 12, v237
	v_bfe_u32 v238, v211, 4, 1
	v_lshl_add_u32 v237, v238, 7, v237
	v_bfe_u32 v238, v211, 2, 2
	v_lshl_add_u32 v237, v238, 5, v237
	v_and_b32_e32 v238, 3, v211
	v_lshl_add_u32 v237, v238, 3, v237
	v_bfe_u32 v237, v211, 1, 3
	v_xor_b32_e32 v237, v235, v237
	v_lshlrev_b32_e32 v237, 4, v237
	v_lshl_add_u32 v237, v234, 7, v237
	v_add_u32_e32 v242, 0x10000, v237
	v_xor_b32_e32 v243, 64, v242
	v_mov_b32_e32 v244, 0
	v_mov_b32_e32 v234, v221
	v_xor_b32_e32 v235, 64, v234
	v_xor_b32_e32 v236, 0x80, v234
	v_xor_b32_e32 v237, 0xc0, v234
	s_lshl_b64 s[98:99], s[82:83], 1
	s_add_u32 s98, s48, s98
	s_addc_u32 s99, s49, s99
	v_readlane_b32 s4, v254, 27
	s_nop 1
	v_add_u32_e32 v245, s4, v218
	v_add_u32_e32 v245, s3, v245
	v_lshlrev_b32_e32 v245, 13, v245
	v_lshl_add_u32 v245, v217, 4, v245
.Lat_loop:
	s_waitcnt vmcnt(0) lgkmcnt(0)
	s_barrier
	s_cmp_gt_u32 s58, s89
	s_cbranch_scc1 .Lat_inactive0
	ds_read_b128 v[162:165], v234
	ds_read_b128 v[166:169], v235
	ds_read_b128 v[170:173], v236
	ds_read_b128 v[174:177], v237
	s_add_i32 m0, s71, 0x0
	s_nop 0
	global_load_lds_dwordx4 v231, s[50:51]
	s_add_i32 m0, s71, 0x400
	s_nop 0
	global_load_lds_dwordx4 v229, s[50:51]
	s_waitcnt lgkmcnt(2)
	v_mfma_f32_16x16x32_bf16 v[130:133], v[162:165], v[178:181], v[246:249]
	v_mfma_f32_16x16x32_bf16 v[146:149], v[162:165], v[194:197], v[250:253]
	ds_read_b128 v[162:165], v234 offset:4096
	v_mfma_f32_16x16x32_bf16 v[130:133], v[166:169], v[182:185], v[130:133]
	s_add_i32 m0, s71, 0x800
	v_mfma_f32_16x16x32_bf16 v[146:149], v[166:169], v[198:201], v[146:149]
	ds_read_b128 v[166:169], v235 offset:4096
	global_load_lds_dwordx4 v227, s[50:51]
	s_waitcnt lgkmcnt(2)
	v_mfma_f32_16x16x32_bf16 v[130:133], v[170:173], v[186:189], v[130:133]
	v_mfma_f32_16x16x32_bf16 v[146:149], v[170:173], v[202:205], v[146:149]
	ds_read_b128 v[170:173], v236 offset:4096
	v_mfma_f32_16x16x32_bf16 v[130:133], v[174:177], v[190:193], v[130:133]
	s_add_i32 m0, s71, 0xc00
	v_mfma_f32_16x16x32_bf16 v[146:149], v[174:177], v[206:209], v[146:149]
	ds_read_b128 v[174:177], v237 offset:4096
	global_load_lds_dwordx4 v225, s[50:51]
	s_waitcnt lgkmcnt(2)
	v_mfma_f32_16x16x32_bf16 v[134:137], v[162:165], v[178:181], v[246:249]
	v_mfma_f32_16x16x32_bf16 v[150:153], v[162:165], v[194:197], v[250:253]
	ds_read_b128 v[162:165], v234 offset:8192
	v_mfma_f32_16x16x32_bf16 v[134:137], v[166:169], v[182:185], v[134:137]
	s_add_i32 m0, s71, 0x1000
	v_mfma_f32_16x16x32_bf16 v[150:153], v[166:169], v[198:201], v[150:153]
	ds_read_b128 v[166:169], v235 offset:8192
	global_load_lds_dwordx4 v230, s[50:51]
	s_waitcnt lgkmcnt(2)
	v_mfma_f32_16x16x32_bf16 v[134:137], v[170:173], v[186:189], v[134:137]
	v_mfma_f32_16x16x32_bf16 v[150:153], v[170:173], v[202:205], v[150:153]
	ds_read_b128 v[170:173], v236 offset:8192
	v_mfma_f32_16x16x32_bf16 v[134:137], v[174:177], v[190:193], v[134:137]
	s_add_i32 m0, s71, 0x1400
	v_mfma_f32_16x16x32_bf16 v[150:153], v[174:177], v[206:209], v[150:153]
	ds_read_b128 v[174:177], v237 offset:8192
	global_load_lds_dwordx4 v228, s[50:51]
	s_waitcnt lgkmcnt(2)
	v_mfma_f32_16x16x32_bf16 v[138:141], v[162:165], v[178:181], v[246:249]
	v_mfma_f32_16x16x32_bf16 v[154:157], v[162:165], v[194:197], v[250:253]
	ds_read_b128 v[162:165], v234 offset:12288
	v_mfma_f32_16x16x32_bf16 v[138:141], v[166:169], v[182:185], v[138:141]
	s_add_i32 m0, s71, 0x1800
	v_mfma_f32_16x16x32_bf16 v[154:157], v[166:169], v[198:201], v[154:157]
	ds_read_b128 v[166:169], v235 offset:12288
	global_load_lds_dwordx4 v226, s[50:51]
	s_waitcnt lgkmcnt(2)
	v_mfma_f32_16x16x32_bf16 v[138:141], v[170:173], v[186:189], v[138:141]
	v_mfma_f32_16x16x32_bf16 v[154:157], v[170:173], v[202:205], v[154:157]
	ds_read_b128 v[170:173], v236 offset:12288
	v_mfma_f32_16x16x32_bf16 v[138:141], v[174:177], v[190:193], v[138:141]
	s_add_i32 m0, s71, 0x1c00
	v_mfma_f32_16x16x32_bf16 v[154:157], v[174:177], v[206:209], v[154:157]
	ds_read_b128 v[174:177], v237 offset:12288
	global_load_lds_dwordx4 v224, s[50:51]
	s_waitcnt lgkmcnt(2)
	v_mfma_f32_16x16x32_bf16 v[142:145], v[162:165], v[178:181], v[246:249]
	v_mfma_f32_16x16x32_bf16 v[158:161], v[162:165], v[194:197], v[250:253]
	ds_read_b128 v[162:165], v242
	v_mfma_f32_16x16x32_bf16 v[142:145], v[166:169], v[182:185], v[142:145]
	v_mfma_f32_16x16x32_bf16 v[158:161], v[166:169], v[198:201], v[158:161]
	ds_read_b128 v[166:169], v243
	s_waitcnt lgkmcnt(2)
	v_mfma_f32_16x16x32_bf16 v[142:145], v[170:173], v[186:189], v[142:145]
	v_mfma_f32_16x16x32_bf16 v[158:161], v[170:173], v[202:205], v[158:161]
	ds_read_b128 v[170:173], v242 offset:2048
	v_mfma_f32_16x16x32_bf16 v[142:145], v[174:177], v[190:193], v[142:145]
	v_mfma_f32_16x16x32_bf16 v[158:161], v[174:177], v[206:209], v[158:161]
	ds_read_b128 v[174:177], v243 offset:2048

.Lat_exp_a:
	v_exp_f32_e32 v130, v130
	v_exp_f32_e32 v131, v131
	v_exp_f32_e32 v132, v132
	v_add_f32_e32 v0, v130, v131
	v_exp_f32_e32 v133, v133
	v_add_f32_e32 v0, v0, v132
	v_exp_f32_e32 v134, v134
	v_add_f32_e32 v0, v0, v133
	v_exp_f32_e32 v135, v135
	v_add_f32_e32 v0, v0, v134
	v_exp_f32_e32 v136, v136
	v_add_f32_e32 v0, v0, v135
	v_exp_f32_e32 v137, v137
	v_add_f32_e32 v0, v0, v136
	v_exp_f32_e32 v138, v138
	v_add_f32_e32 v0, v0, v137
	v_exp_f32_e32 v139, v139
	v_add_f32_e32 v0, v0, v138
	v_exp_f32_e32 v140, v140
	v_add_f32_e32 v0, v0, v139
	v_exp_f32_e32 v141, v141
	v_add_f32_e32 v0, v0, v140
	v_exp_f32_e32 v142, v142
	v_add_f32_e32 v0, v0, v141
	v_exp_f32_e32 v143, v143
	v_add_f32_e32 v0, v0, v142
	v_exp_f32_e32 v144, v144
	v_add_f32_e32 v0, v0, v143
	v_exp_f32_e32 v145, v145
	v_add_f32_e32 v0, v0, v144
	v_exp_f32_e32 v146, v146
	v_exp_f32_e32 v147, v147
	v_exp_f32_e32 v148, v148
	v_add_f32_e32 v233, v146, v147
	v_exp_f32_e32 v149, v149
	v_add_f32_e32 v233, v233, v148
	v_exp_f32_e32 v150, v150
	v_add_f32_e32 v233, v233, v149
	v_exp_f32_e32 v151, v151
	v_add_f32_e32 v233, v233, v150
	v_exp_f32_e32 v152, v152
	v_add_f32_e32 v233, v233, v151
	v_exp_f32_e32 v153, v153
	v_add_f32_e32 v233, v233, v152
	v_exp_f32_e32 v154, v154
	v_add_f32_e32 v233, v233, v153
	v_exp_f32_e32 v155, v155
	v_add_f32_e32 v233, v233, v154
	v_exp_f32_e32 v156, v156
	v_add_f32_e32 v233, v233, v155
	v_exp_f32_e32 v157, v157
	v_add_f32_e32 v233, v233, v156
	v_exp_f32_e32 v158, v158
	v_add_f32_e32 v233, v233, v157
	v_exp_f32_e32 v159, v159
	v_add_f32_e32 v233, v233, v158
	v_exp_f32_e32 v160, v160
	v_add_f32_e32 v233, v233, v159
	v_exp_f32_e32 v161, v161
	v_add_f32_e32 v233, v233, v160
	v_add_f32_e32 v0, v0, v145
	v_add_f32_e32 v233, v233, v161
	v_max_f32_e32 v238, v0, v233
	v_cmp_ge_f32_e32 vcc, 0x43800000, v238
	s_cmp_eq_u64 vcc, exec
	s_cbranch_scc0 .Lat_redo_a
	v_add_f32_e32 v232, v232, v0
	v_cvt_pk_bf16_f32 v130, v130, v131
	v_cvt_pk_bf16_f32 v131, v132, v133
	v_cvt_pk_bf16_f32 v132, v134, v135
	v_cvt_pk_bf16_f32 v133, v136, v137
	v_cvt_pk_bf16_f32 v134, v138, v139
	v_cvt_pk_bf16_f32 v135, v140, v141
	v_cvt_pk_bf16_f32 v136, v142, v143
	v_cvt_pk_bf16_f32 v137, v144, v145
	v_add_f32_e32 v244, v244, v233
	v_cvt_pk_bf16_f32 v146, v146, v147
	v_cvt_pk_bf16_f32 v147, v148, v149
	v_cvt_pk_bf16_f32 v148, v150, v151
	v_cvt_pk_bf16_f32 v149, v152, v153
	v_cvt_pk_bf16_f32 v150, v154, v155
	v_cvt_pk_bf16_f32 v151, v156, v157
	v_cvt_pk_bf16_f32 v152, v158, v159
	v_cvt_pk_bf16_f32 v153, v160, v161
	s_waitcnt lgkmcnt(2)
	v_mfma_f32_16x16x32_bf16 v[114:117], v[162:165], v[130:133], v[114:117]
	v_mfma_f32_16x16x32_bf16 v[122:125], v[162:165], v[146:149], v[122:125]
	ds_read_b128 v[162:165], v242 offset:4096
	v_mfma_f32_16x16x32_bf16 v[114:117], v[166:169], v[134:137], v[114:117]
	v_mfma_f32_16x16x32_bf16 v[122:125], v[166:169], v[150:153], v[122:125]
	ds_read_b128 v[166:169], v243 offset:4096
	s_waitcnt lgkmcnt(2)
	v_mfma_f32_16x16x32_bf16 v[118:121], v[170:173], v[130:133], v[118:121]
	v_mfma_f32_16x16x32_bf16 v[126:129], v[170:173], v[146:149], v[126:129]
	ds_read_b128 v[170:173], v242 offset:6144
	v_mfma_f32_16x16x32_bf16 v[118:121], v[174:177], v[134:137], v[118:121]
	v_mfma_f32_16x16x32_bf16 v[126:129], v[174:177], v[150:153], v[126:129]
	ds_read_b128 v[174:177], v243 offset:6144
	s_waitcnt lgkmcnt(2)
	v_mfma_f32_16x16x32_bf16 v[98:101], v[162:165], v[130:133], v[98:101]
	v_mfma_f32_16x16x32_bf16 v[106:109], v[162:165], v[146:149], v[106:109]
	ds_read_b128 v[162:165], v242 offset:8192
	v_mfma_f32_16x16x32_bf16 v[98:101], v[166:169], v[134:137], v[98:101]
	v_mfma_f32_16x16x32_bf16 v[106:109], v[166:169], v[150:153], v[106:109]
	ds_read_b128 v[166:169], v243 offset:8192
	s_waitcnt lgkmcnt(2)
	v_mfma_f32_16x16x32_bf16 v[102:105], v[170:173], v[130:133], v[102:105]
	v_mfma_f32_16x16x32_bf16 v[110:113], v[170:173], v[146:149], v[110:113]
	ds_read_b128 v[170:173], v242 offset:10240
	v_mfma_f32_16x16x32_bf16 v[102:105], v[174:177], v[134:137], v[102:105]
	v_mfma_f32_16x16x32_bf16 v[110:113], v[174:177], v[150:153], v[110:113]
	ds_read_b128 v[174:177], v243 offset:10240
	s_waitcnt lgkmcnt(2)
	v_mfma_f32_16x16x32_bf16 v[82:85], v[162:165], v[130:133], v[82:85]
	v_mfma_f32_16x16x32_bf16 v[90:93], v[162:165], v[146:149], v[90:93]
	ds_read_b128 v[162:165], v242 offset:12288
	v_mfma_f32_16x16x32_bf16 v[82:85], v[166:169], v[134:137], v[82:85]
	v_mfma_f32_16x16x32_bf16 v[90:93], v[166:169], v[150:153], v[90:93]
	ds_read_b128 v[166:169], v243 offset:12288
	s_waitcnt lgkmcnt(2)
	v_mfma_f32_16x16x32_bf16 v[86:89], v[170:173], v[130:133], v[86:89]
	v_mfma_f32_16x16x32_bf16 v[94:97], v[170:173], v[146:149], v[94:97]
	ds_read_b128 v[170:173], v242 offset:14336
	v_mfma_f32_16x16x32_bf16 v[86:89], v[174:177], v[134:137], v[86:89]
	v_mfma_f32_16x16x32_bf16 v[94:97], v[174:177], v[150:153], v[94:97]
	ds_read_b128 v[174:177], v243 offset:14336
	s_waitcnt lgkmcnt(2)
	v_mfma_f32_16x16x32_bf16 v[66:69], v[162:165], v[130:133], v[66:69]
	v_mfma_f32_16x16x32_bf16 v[74:77], v[162:165], v[146:149], v[74:77]
	ds_read_b128 v[162:165], v242 offset:16384
	v_mfma_f32_16x16x32_bf16 v[66:69], v[166:169], v[134:137], v[66:69]
	v_mfma_f32_16x16x32_bf16 v[74:77], v[166:169], v[150:153], v[74:77]
	ds_read_b128 v[166:169], v243 offset:16384
	s_waitcnt lgkmcnt(2)
	v_mfma_f32_16x16x32_bf16 v[70:73], v[170:173], v[130:133], v[70:73]
	v_mfma_f32_16x16x32_bf16 v[78:81], v[170:173], v[146:149], v[78:81]
	ds_read_b128 v[170:173], v242 offset:18432
	v_mfma_f32_16x16x32_bf16 v[70:73], v[174:177], v[134:137], v[70:73]
	v_mfma_f32_16x16x32_bf16 v[78:81], v[174:177], v[150:153], v[78:81]
	ds_read_b128 v[174:177], v243 offset:18432
	s_waitcnt lgkmcnt(2)
	v_mfma_f32_16x16x32_bf16 v[50:53], v[162:165], v[130:133], v[50:53]
	v_mfma_f32_16x16x32_bf16 v[58:61], v[162:165], v[146:149], v[58:61]
	ds_read_b128 v[162:165], v242 offset:20480
	v_mfma_f32_16x16x32_bf16 v[50:53], v[166:169], v[134:137], v[50:53]
	v_mfma_f32_16x16x32_bf16 v[58:61], v[166:169], v[150:153], v[58:61]
	ds_read_b128 v[166:169], v243 offset:20480
	s_waitcnt lgkmcnt(2)
	v_mfma_f32_16x16x32_bf16 v[54:57], v[170:173], v[130:133], v[54:57]
	v_mfma_f32_16x16x32_bf16 v[62:65], v[170:173], v[146:149], v[62:65]
	ds_read_b128 v[170:173], v242 offset:22528
	v_mfma_f32_16x16x32_bf16 v[54:57], v[174:177], v[134:137], v[54:57]
	v_mfma_f32_16x16x32_bf16 v[62:65], v[174:177], v[150:153], v[62:65]
	ds_read_b128 v[174:177], v243 offset:22528
	s_waitcnt lgkmcnt(2)
	v_mfma_f32_16x16x32_bf16 v[34:37], v[162:165], v[130:133], v[34:37]
	v_mfma_f32_16x16x32_bf16 v[42:45], v[162:165], v[146:149], v[42:45]
	ds_read_b128 v[162:165], v242 offset:24576
	v_mfma_f32_16x16x32_bf16 v[34:37], v[166:169], v[134:137], v[34:37]
	v_mfma_f32_16x16x32_bf16 v[42:45], v[166:169], v[150:153], v[42:45]
	ds_read_b128 v[166:169], v243 offset:24576
	s_waitcnt lgkmcnt(2)
	v_mfma_f32_16x16x32_bf16 v[38:41], v[170:173], v[130:133], v[38:41]
	v_mfma_f32_16x16x32_bf16 v[46:49], v[170:173], v[146:149], v[46:49]
	ds_read_b128 v[170:173], v242 offset:26624
	v_mfma_f32_16x16x32_bf16 v[38:41], v[174:177], v[134:137], v[38:41]
	v_mfma_f32_16x16x32_bf16 v[46:49], v[174:177], v[150:153], v[46:49]
	ds_read_b128 v[174:177], v243 offset:26624
	s_waitcnt lgkmcnt(2)
	v_mfma_f32_16x16x32_bf16 v[18:21], v[162:165], v[130:133], v[18:21]
	v_mfma_f32_16x16x32_bf16 v[26:29], v[162:165], v[146:149], v[26:29]
	ds_read_b128 v[162:165], v242 offset:28672
	v_mfma_f32_16x16x32_bf16 v[18:21], v[166:169], v[134:137], v[18:21]
	v_mfma_f32_16x16x32_bf16 v[26:29], v[166:169], v[150:153], v[26:29]
	ds_read_b128 v[166:169], v243 offset:28672
	s_waitcnt lgkmcnt(2)
	v_mfma_f32_16x16x32_bf16 v[22:25], v[170:173], v[130:133], v[22:25]
	v_mfma_f32_16x16x32_bf16 v[30:33], v[170:173], v[146:149], v[30:33]
	ds_read_b128 v[170:173], v242 offset:30720
	v_mfma_f32_16x16x32_bf16 v[22:25], v[174:177], v[134:137], v[22:25]
	v_mfma_f32_16x16x32_bf16 v[30:33], v[174:177], v[150:153], v[30:33]
	ds_read_b128 v[174:177], v243 offset:30720
	s_waitcnt lgkmcnt(2)
	v_mfma_f32_16x16x32_bf16 v[2:5], v[162:165], v[130:133], v[2:5]
	v_mfma_f32_16x16x32_bf16 v[10:13], v[162:165], v[146:149], v[10:13]
	v_mfma_f32_16x16x32_bf16 v[2:5], v[166:169], v[134:137], v[2:5]
	v_mfma_f32_16x16x32_bf16 v[10:13], v[166:169], v[150:153], v[10:13]
	s_waitcnt lgkmcnt(0)
	v_mfma_f32_16x16x32_bf16 v[6:9], v[170:173], v[130:133], v[6:9]
	v_mfma_f32_16x16x32_bf16 v[14:17], v[170:173], v[146:149], v[14:17]
	v_mfma_f32_16x16x32_bf16 v[6:9], v[174:177], v[134:137], v[6:9]
	v_mfma_f32_16x16x32_bf16 v[14:17], v[174:177], v[150:153], v[14:17]
	s_branch .Lat_end_a

.Lat_end_a:
.Lat_next0:
	s_add_i32 s58, s58, 1
	v_add_u32_e32 v223, 0xffffffc0, v223
	s_addk_i32 s91, 0x40
	s_add_u32 s50, s50, s100
	s_addc_u32 s51, s51, 0
	s_mov_b32 s94, 0
	s_cmp_gt_u32 s58, s88
	s_cbranch_scc1 .Lat_final
	s_waitcnt vmcnt(0) lgkmcnt(0)
	s_barrier
	s_cmp_gt_u32 s58, s89
	s_cbranch_scc1 .Lat_inactive1
	ds_read_b128 v[162:165], v234 offset:32768
	ds_read_b128 v[166:169], v235 offset:32768
	ds_read_b128 v[170:173], v236 offset:32768
	ds_read_b128 v[174:177], v237 offset:32768
	s_add_i32 m0, s97, 0x0
	s_nop 0
	global_load_lds_dwordx4 v231, s[50:51]
	s_add_i32 m0, s97, 0x400
	s_nop 0
	global_load_lds_dwordx4 v229, s[50:51]
	s_waitcnt lgkmcnt(2)
	v_mfma_f32_16x16x32_bf16 v[130:133], v[162:165], v[178:181], v[246:249]
	v_mfma_f32_16x16x32_bf16 v[146:149], v[162:165], v[194:197], v[250:253]
	ds_read_b128 v[162:165], v234 offset:36864
	v_mfma_f32_16x16x32_bf16 v[130:133], v[166:169], v[182:185], v[130:133]
	s_add_i32 m0, s97, 0x800
	v_mfma_f32_16x16x32_bf16 v[146:149], v[166:169], v[198:201], v[146:149]
	ds_read_b128 v[166:169], v235 offset:36864
	global_load_lds_dwordx4 v227, s[50:51]
	s_waitcnt lgkmcnt(2)
	v_mfma_f32_16x16x32_bf16 v[130:133], v[170:173], v[186:189], v[130:133]
	v_mfma_f32_16x16x32_bf16 v[146:149], v[170:173], v[202:205], v[146:149]
	ds_read_b128 v[170:173], v236 offset:36864
	v_mfma_f32_16x16x32_bf16 v[130:133], v[174:177], v[190:193], v[130:133]
	s_add_i32 m0, s97, 0xc00
	v_mfma_f32_16x16x32_bf16 v[146:149], v[174:177], v[206:209], v[146:149]
	ds_read_b128 v[174:177], v237 offset:36864
	global_load_lds_dwordx4 v225, s[50:51]
	s_waitcnt lgkmcnt(2)
	v_mfma_f32_16x16x32_bf16 v[134:137], v[162:165], v[178:181], v[246:249]
	v_mfma_f32_16x16x32_bf16 v[150:153], v[162:165], v[194:197], v[250:253]
	ds_read_b128 v[162:165], v234 offset:40960
	v_mfma_f32_16x16x32_bf16 v[134:137], v[166:169], v[182:185], v[134:137]
	s_add_i32 m0, s97, 0x1000
	v_mfma_f32_16x16x32_bf16 v[150:153], v[166:169], v[198:201], v[150:153]
	ds_read_b128 v[166:169], v235 offset:40960
	global_load_lds_dwordx4 v230, s[50:51]
	s_waitcnt lgkmcnt(2)
	v_mfma_f32_16x16x32_bf16 v[134:137], v[170:173], v[186:189], v[134:137]
	v_mfma_f32_16x16x32_bf16 v[150:153], v[170:173], v[202:205], v[150:153]
	ds_read_b128 v[170:173], v236 offset:40960
	v_mfma_f32_16x16x32_bf16 v[134:137], v[174:177], v[190:193], v[134:137]
	s_add_i32 m0, s97, 0x1400
	v_mfma_f32_16x16x32_bf16 v[150:153], v[174:177], v[206:209], v[150:153]
	ds_read_b128 v[174:177], v237 offset:40960
	global_load_lds_dwordx4 v228, s[50:51]
	s_waitcnt lgkmcnt(2)
	v_mfma_f32_16x16x32_bf16 v[138:141], v[162:165], v[178:181], v[246:249]
	v_mfma_f32_16x16x32_bf16 v[154:157], v[162:165], v[194:197], v[250:253]
	ds_read_b128 v[162:165], v234 offset:45056
	v_mfma_f32_16x16x32_bf16 v[138:141], v[166:169], v[182:185], v[138:141]
	s_add_i32 m0, s97, 0x1800
	v_mfma_f32_16x16x32_bf16 v[154:157], v[166:169], v[198:201], v[154:157]
	ds_read_b128 v[166:169], v235 offset:45056
	global_load_lds_dwordx4 v226, s[50:51]
	s_waitcnt lgkmcnt(2)
	v_mfma_f32_16x16x32_bf16 v[138:141], v[170:173], v[186:189], v[138:141]
	v_mfma_f32_16x16x32_bf16 v[154:157], v[170:173], v[202:205], v[154:157]
	ds_read_b128 v[170:173], v236 offset:45056
	v_mfma_f32_16x16x32_bf16 v[138:141], v[174:177], v[190:193], v[138:141]
	s_add_i32 m0, s97, 0x1c00
	v_mfma_f32_16x16x32_bf16 v[154:157], v[174:177], v[206:209], v[154:157]
	ds_read_b128 v[174:177], v237 offset:45056
	global_load_lds_dwordx4 v224, s[50:51]
	s_waitcnt lgkmcnt(2)
	v_mfma_f32_16x16x32_bf16 v[142:145], v[162:165], v[178:181], v[246:249]
	v_mfma_f32_16x16x32_bf16 v[158:161], v[162:165], v[194:197], v[250:253]
	ds_read_b128 v[162:165], v242 offset:32768
	v_mfma_f32_16x16x32_bf16 v[142:145], v[166:169], v[182:185], v[142:145]
	v_mfma_f32_16x16x32_bf16 v[158:161], v[166:169], v[198:201], v[158:161]
	ds_read_b128 v[166:169], v243 offset:32768
	s_waitcnt lgkmcnt(2)
	v_mfma_f32_16x16x32_bf16 v[142:145], v[170:173], v[186:189], v[142:145]
	v_mfma_f32_16x16x32_bf16 v[158:161], v[170:173], v[202:205], v[158:161]
	ds_read_b128 v[170:173], v242 offset:34816
	v_mfma_f32_16x16x32_bf16 v[142:145], v[174:177], v[190:193], v[142:145]
	v_mfma_f32_16x16x32_bf16 v[158:161], v[174:177], v[206:209], v[158:161]
	ds_read_b128 v[174:177], v243 offset:34816

.Lat_exp_c:
	v_exp_f32_e32 v130, v130
	v_exp_f32_e32 v131, v131
	v_exp_f32_e32 v132, v132
	v_add_f32_e32 v0, v130, v131
	v_exp_f32_e32 v133, v133
	v_add_f32_e32 v0, v0, v132
	v_exp_f32_e32 v134, v134
	v_add_f32_e32 v0, v0, v133
	v_exp_f32_e32 v135, v135
	v_add_f32_e32 v0, v0, v134
	v_exp_f32_e32 v136, v136
	v_add_f32_e32 v0, v0, v135
	v_exp_f32_e32 v137, v137
	v_add_f32_e32 v0, v0, v136
	v_exp_f32_e32 v138, v138
	v_add_f32_e32 v0, v0, v137
	v_exp_f32_e32 v139, v139
	v_add_f32_e32 v0, v0, v138
	v_exp_f32_e32 v140, v140
	v_add_f32_e32 v0, v0, v139
	v_exp_f32_e32 v141, v141
	v_add_f32_e32 v0, v0, v140
	v_exp_f32_e32 v142, v142
	v_add_f32_e32 v0, v0, v141
	v_exp_f32_e32 v143, v143
	v_add_f32_e32 v0, v0, v142
	v_exp_f32_e32 v144, v144
	v_add_f32_e32 v0, v0, v143
	v_exp_f32_e32 v145, v145
	v_add_f32_e32 v0, v0, v144
	v_exp_f32_e32 v146, v146
	v_exp_f32_e32 v147, v147
	v_exp_f32_e32 v148, v148
	v_add_f32_e32 v233, v146, v147
	v_exp_f32_e32 v149, v149
	v_add_f32_e32 v233, v233, v148
	v_exp_f32_e32 v150, v150
	v_add_f32_e32 v233, v233, v149
	v_exp_f32_e32 v151, v151
	v_add_f32_e32 v233, v233, v150
	v_exp_f32_e32 v152, v152
	v_add_f32_e32 v233, v233, v151
	v_exp_f32_e32 v153, v153
	v_add_f32_e32 v233, v233, v152
	v_exp_f32_e32 v154, v154
	v_add_f32_e32 v233, v233, v153
	v_exp_f32_e32 v155, v155
	v_add_f32_e32 v233, v233, v154
	v_exp_f32_e32 v156, v156
	v_add_f32_e32 v233, v233, v155
	v_exp_f32_e32 v157, v157
	v_add_f32_e32 v233, v233, v156
	v_exp_f32_e32 v158, v158
	v_add_f32_e32 v233, v233, v157
	v_exp_f32_e32 v159, v159
	v_add_f32_e32 v233, v233, v158
	v_exp_f32_e32 v160, v160
	v_add_f32_e32 v233, v233, v159
	v_exp_f32_e32 v161, v161
	v_add_f32_e32 v233, v233, v160
	v_add_f32_e32 v0, v0, v145
	v_add_f32_e32 v233, v233, v161
	v_max_f32_e32 v238, v0, v233
	v_cmp_ge_f32_e32 vcc, 0x43800000, v238
	s_cmp_eq_u64 vcc, exec
	s_cbranch_scc0 .Lat_redo_c
	v_add_f32_e32 v232, v232, v0
	v_cvt_pk_bf16_f32 v130, v130, v131
	v_cvt_pk_bf16_f32 v131, v132, v133
	v_cvt_pk_bf16_f32 v132, v134, v135
	v_cvt_pk_bf16_f32 v133, v136, v137
	v_cvt_pk_bf16_f32 v134, v138, v139
	v_cvt_pk_bf16_f32 v135, v140, v141
	v_cvt_pk_bf16_f32 v136, v142, v143
	v_cvt_pk_bf16_f32 v137, v144, v145
	v_add_f32_e32 v244, v244, v233
	v_cvt_pk_bf16_f32 v146, v146, v147
	v_cvt_pk_bf16_f32 v147, v148, v149
	v_cvt_pk_bf16_f32 v148, v150, v151
	v_cvt_pk_bf16_f32 v149, v152, v153
	v_cvt_pk_bf16_f32 v150, v154, v155
	v_cvt_pk_bf16_f32 v151, v156, v157
	v_cvt_pk_bf16_f32 v152, v158, v159
	v_cvt_pk_bf16_f32 v153, v160, v161
	s_waitcnt lgkmcnt(2)
	v_mfma_f32_16x16x32_bf16 v[114:117], v[162:165], v[130:133], v[114:117]
	v_mfma_f32_16x16x32_bf16 v[122:125], v[162:165], v[146:149], v[122:125]
	ds_read_b128 v[162:165], v242 offset:36864
	v_mfma_f32_16x16x32_bf16 v[114:117], v[166:169], v[134:137], v[114:117]
	v_mfma_f32_16x16x32_bf16 v[122:125], v[166:169], v[150:153], v[122:125]
	ds_read_b128 v[166:169], v243 offset:36864
	s_waitcnt lgkmcnt(2)
	v_mfma_f32_16x16x32_bf16 v[118:121], v[170:173], v[130:133], v[118:121]
	v_mfma_f32_16x16x32_bf16 v[126:129], v[170:173], v[146:149], v[126:129]
	ds_read_b128 v[170:173], v242 offset:38912
	v_mfma_f32_16x16x32_bf16 v[118:121], v[174:177], v[134:137], v[118:121]
	v_mfma_f32_16x16x32_bf16 v[126:129], v[174:177], v[150:153], v[126:129]
	ds_read_b128 v[174:177], v243 offset:38912
	s_waitcnt lgkmcnt(2)
	v_mfma_f32_16x16x32_bf16 v[98:101], v[162:165], v[130:133], v[98:101]
	v_mfma_f32_16x16x32_bf16 v[106:109], v[162:165], v[146:149], v[106:109]
	ds_read_b128 v[162:165], v242 offset:40960
	v_mfma_f32_16x16x32_bf16 v[98:101], v[166:169], v[134:137], v[98:101]
	v_mfma_f32_16x16x32_bf16 v[106:109], v[166:169], v[150:153], v[106:109]
	ds_read_b128 v[166:169], v243 offset:40960
	s_waitcnt lgkmcnt(2)
	v_mfma_f32_16x16x32_bf16 v[102:105], v[170:173], v[130:133], v[102:105]
	v_mfma_f32_16x16x32_bf16 v[110:113], v[170:173], v[146:149], v[110:113]
	ds_read_b128 v[170:173], v242 offset:43008
	v_mfma_f32_16x16x32_bf16 v[102:105], v[174:177], v[134:137], v[102:105]
	v_mfma_f32_16x16x32_bf16 v[110:113], v[174:177], v[150:153], v[110:113]
	ds_read_b128 v[174:177], v243 offset:43008
	s_waitcnt lgkmcnt(2)
	v_mfma_f32_16x16x32_bf16 v[82:85], v[162:165], v[130:133], v[82:85]
	v_mfma_f32_16x16x32_bf16 v[90:93], v[162:165], v[146:149], v[90:93]
	ds_read_b128 v[162:165], v242 offset:45056
	v_mfma_f32_16x16x32_bf16 v[82:85], v[166:169], v[134:137], v[82:85]
	v_mfma_f32_16x16x32_bf16 v[90:93], v[166:169], v[150:153], v[90:93]
	ds_read_b128 v[166:169], v243 offset:45056
	s_waitcnt lgkmcnt(2)
	v_mfma_f32_16x16x32_bf16 v[86:89], v[170:173], v[130:133], v[86:89]
	v_mfma_f32_16x16x32_bf16 v[94:97], v[170:173], v[146:149], v[94:97]
	ds_read_b128 v[170:173], v242 offset:47104
	v_mfma_f32_16x16x32_bf16 v[86:89], v[174:177], v[134:137], v[86:89]
	v_mfma_f32_16x16x32_bf16 v[94:97], v[174:177], v[150:153], v[94:97]
	ds_read_b128 v[174:177], v243 offset:47104
	s_waitcnt lgkmcnt(2)
	v_mfma_f32_16x16x32_bf16 v[66:69], v[162:165], v[130:133], v[66:69]
	v_mfma_f32_16x16x32_bf16 v[74:77], v[162:165], v[146:149], v[74:77]
	ds_read_b128 v[162:165], v242 offset:49152
	v_mfma_f32_16x16x32_bf16 v[66:69], v[166:169], v[134:137], v[66:69]
	v_mfma_f32_16x16x32_bf16 v[74:77], v[166:169], v[150:153], v[74:77]
	ds_read_b128 v[166:169], v243 offset:49152
	s_waitcnt lgkmcnt(2)
	v_mfma_f32_16x16x32_bf16 v[70:73], v[170:173], v[130:133], v[70:73]
	v_mfma_f32_16x16x32_bf16 v[78:81], v[170:173], v[146:149], v[78:81]
	ds_read_b128 v[170:173], v242 offset:51200
	v_mfma_f32_16x16x32_bf16 v[70:73], v[174:177], v[134:137], v[70:73]
	v_mfma_f32_16x16x32_bf16 v[78:81], v[174:177], v[150:153], v[78:81]
	ds_read_b128 v[174:177], v243 offset:51200
	s_waitcnt lgkmcnt(2)
	v_mfma_f32_16x16x32_bf16 v[50:53], v[162:165], v[130:133], v[50:53]
	v_mfma_f32_16x16x32_bf16 v[58:61], v[162:165], v[146:149], v[58:61]
	ds_read_b128 v[162:165], v242 offset:53248
	v_mfma_f32_16x16x32_bf16 v[50:53], v[166:169], v[134:137], v[50:53]
	v_mfma_f32_16x16x32_bf16 v[58:61], v[166:169], v[150:153], v[58:61]
	ds_read_b128 v[166:169], v243 offset:53248
	s_waitcnt lgkmcnt(2)
	v_mfma_f32_16x16x32_bf16 v[54:57], v[170:173], v[130:133], v[54:57]
	v_mfma_f32_16x16x32_bf16 v[62:65], v[170:173], v[146:149], v[62:65]
	ds_read_b128 v[170:173], v242 offset:55296
	v_mfma_f32_16x16x32_bf16 v[54:57], v[174:177], v[134:137], v[54:57]
	v_mfma_f32_16x16x32_bf16 v[62:65], v[174:177], v[150:153], v[62:65]
	ds_read_b128 v[174:177], v243 offset:55296
	s_waitcnt lgkmcnt(2)
	v_mfma_f32_16x16x32_bf16 v[34:37], v[162:165], v[130:133], v[34:37]
	v_mfma_f32_16x16x32_bf16 v[42:45], v[162:165], v[146:149], v[42:45]
	ds_read_b128 v[162:165], v242 offset:57344
	v_mfma_f32_16x16x32_bf16 v[34:37], v[166:169], v[134:137], v[34:37]
	v_mfma_f32_16x16x32_bf16 v[42:45], v[166:169], v[150:153], v[42:45]
	ds_read_b128 v[166:169], v243 offset:57344
	s_waitcnt lgkmcnt(2)
	v_mfma_f32_16x16x32_bf16 v[38:41], v[170:173], v[130:133], v[38:41]
	v_mfma_f32_16x16x32_bf16 v[46:49], v[170:173], v[146:149], v[46:49]
	ds_read_b128 v[170:173], v242 offset:59392
	v_mfma_f32_16x16x32_bf16 v[38:41], v[174:177], v[134:137], v[38:41]
	v_mfma_f32_16x16x32_bf16 v[46:49], v[174:177], v[150:153], v[46:49]
	ds_read_b128 v[174:177], v243 offset:59392
	s_waitcnt lgkmcnt(2)
	v_mfma_f32_16x16x32_bf16 v[18:21], v[162:165], v[130:133], v[18:21]
	v_mfma_f32_16x16x32_bf16 v[26:29], v[162:165], v[146:149], v[26:29]
	ds_read_b128 v[162:165], v242 offset:61440
	v_mfma_f32_16x16x32_bf16 v[18:21], v[166:169], v[134:137], v[18:21]
	v_mfma_f32_16x16x32_bf16 v[26:29], v[166:169], v[150:153], v[26:29]
	ds_read_b128 v[166:169], v243 offset:61440
	s_waitcnt lgkmcnt(2)
	v_mfma_f32_16x16x32_bf16 v[22:25], v[170:173], v[130:133], v[22:25]
	v_mfma_f32_16x16x32_bf16 v[30:33], v[170:173], v[146:149], v[30:33]
	ds_read_b128 v[170:173], v242 offset:63488
	v_mfma_f32_16x16x32_bf16 v[22:25], v[174:177], v[134:137], v[22:25]
	v_mfma_f32_16x16x32_bf16 v[30:33], v[174:177], v[150:153], v[30:33]
	ds_read_b128 v[174:177], v243 offset:63488
	s_waitcnt lgkmcnt(2)
	v_mfma_f32_16x16x32_bf16 v[2:5], v[162:165], v[130:133], v[2:5]
	v_mfma_f32_16x16x32_bf16 v[10:13], v[162:165], v[146:149], v[10:13]
	v_mfma_f32_16x16x32_bf16 v[2:5], v[166:169], v[134:137], v[2:5]
	v_mfma_f32_16x16x32_bf16 v[10:13], v[166:169], v[150:153], v[10:13]
	s_waitcnt lgkmcnt(0)
	v_mfma_f32_16x16x32_bf16 v[6:9], v[170:173], v[130:133], v[6:9]
	v_mfma_f32_16x16x32_bf16 v[14:17], v[170:173], v[146:149], v[14:17]
	v_mfma_f32_16x16x32_bf16 v[6:9], v[174:177], v[134:137], v[6:9]
	v_mfma_f32_16x16x32_bf16 v[14:17], v[174:177], v[150:153], v[14:17]
	s_branch .Lat_end_c

.Lat_end_c:
.Lat_next1:
	s_add_i32 s58, s58, 1
	v_add_u32_e32 v223, 0xffffffc0, v223
	s_addk_i32 s91, 0x40
	s_add_u32 s50, s50, s100
	s_addc_u32 s51, s51, 0
	s_mov_b32 s94, 0
	s_branch .Lat_loop
.Lat_final:
	s_waitcnt vmcnt(0) lgkmcnt(0)
	s_barrier
	s_add_i32 m0, s97, 0x0
	s_nop 0
	global_load_lds_dwordx4 v245, s[98:99]
	s_add_i32 m0, s97, 0x400
	v_add_u32_e32 v245, 0x4000, v245
	global_load_lds_dwordx4 v245, s[98:99]
	s_add_i32 m0, s97, 0x800
	v_add_u32_e32 v245, 0x4000, v245
	global_load_lds_dwordx4 v245, s[98:99]
	s_add_i32 m0, s97, 0xc00
	v_add_u32_e32 v245, 0x4000, v245
	global_load_lds_dwordx4 v245, s[98:99]
	s_add_i32 m0, s97, 0x1000
	v_add_u32_e32 v245, 0x4000, v245
	global_load_lds_dwordx4 v245, s[98:99]
	s_add_i32 m0, s97, 0x1400
	v_add_u32_e32 v245, 0x4000, v245
	global_load_lds_dwordx4 v245, s[98:99]
	s_add_i32 m0, s97, 0x1800
	v_add_u32_e32 v245, 0x4000, v245
	global_load_lds_dwordx4 v245, s[98:99]
	s_add_i32 m0, s97, 0x1c00
	v_add_u32_e32 v245, 0x4000, v245
	global_load_lds_dwordx4 v245, s[98:99]
	s_cmp_gt_u32 s58, s89
	s_cbranch_scc1 .Lat_done
	ds_read_b128 v[162:165], v234 offset:32768
	ds_read_b128 v[166:169], v235 offset:32768
	ds_read_b128 v[170:173], v236 offset:32768
	ds_read_b128 v[174:177], v237 offset:32768
	s_waitcnt lgkmcnt(2)
	v_mfma_f32_16x16x32_bf16 v[130:133], v[162:165], v[178:181], v[246:249]
	v_mfma_f32_16x16x32_bf16 v[146:149], v[162:165], v[194:197], v[250:253]
	ds_read_b128 v[162:165], v234 offset:36864
	v_mfma_f32_16x16x32_bf16 v[130:133], v[166:169], v[182:185], v[130:133]
	v_mfma_f32_16x16x32_bf16 v[146:149], v[166:169], v[198:201], v[146:149]
	ds_read_b128 v[166:169], v235 offset:36864
	s_waitcnt lgkmcnt(2)
	v_mfma_f32_16x16x32_bf16 v[130:133], v[170:173], v[186:189], v[130:133]
	v_mfma_f32_16x16x32_bf16 v[146:149], v[170:173], v[202:205], v[146:149]
	ds_read_b128 v[170:173], v236 offset:36864
	v_mfma_f32_16x16x32_bf16 v[130:133], v[174:177], v[190:193], v[130:133]
	v_mfma_f32_16x16x32_bf16 v[146:149], v[174:177], v[206:209], v[146:149]
	ds_read_b128 v[174:177], v237 offset:36864
	s_waitcnt lgkmcnt(2)
	v_mfma_f32_16x16x32_bf16 v[134:137], v[162:165], v[178:181], v[246:249]
	v_mfma_f32_16x16x32_bf16 v[150:153], v[162:165], v[194:197], v[250:253]
	ds_read_b128 v[162:165], v234 offset:40960
	v_mfma_f32_16x16x32_bf16 v[134:137], v[166:169], v[182:185], v[134:137]
	v_mfma_f32_16x16x32_bf16 v[150:153], v[166:169], v[198:201], v[150:153]
	ds_read_b128 v[166:169], v235 offset:40960
	s_waitcnt lgkmcnt(2)
	v_mfma_f32_16x16x32_bf16 v[134:137], v[170:173], v[186:189], v[134:137]
	v_mfma_f32_16x16x32_bf16 v[150:153], v[170:173], v[202:205], v[150:153]
	ds_read_b128 v[170:173], v236 offset:40960
	v_mfma_f32_16x16x32_bf16 v[134:137], v[174:177], v[190:193], v[134:137]
	v_mfma_f32_16x16x32_bf16 v[150:153], v[174:177], v[206:209], v[150:153]
	ds_read_b128 v[174:177], v237 offset:40960
	s_waitcnt lgkmcnt(2)
	v_mfma_f32_16x16x32_bf16 v[138:141], v[162:165], v[178:181], v[246:249]
	v_mfma_f32_16x16x32_bf16 v[154:157], v[162:165], v[194:197], v[250:253]
	ds_read_b128 v[162:165], v234 offset:45056
	v_mfma_f32_16x16x32_bf16 v[138:141], v[166:169], v[182:185], v[138:141]
	v_mfma_f32_16x16x32_bf16 v[154:157], v[166:169], v[198:201], v[154:157]
	ds_read_b128 v[166:169], v235 offset:45056
	s_waitcnt lgkmcnt(2)
	v_mfma_f32_16x16x32_bf16 v[138:141], v[170:173], v[186:189], v[138:141]
	v_mfma_f32_16x16x32_bf16 v[154:157], v[170:173], v[202:205], v[154:157]
	ds_read_b128 v[170:173], v236 offset:45056
	v_mfma_f32_16x16x32_bf16 v[138:141], v[174:177], v[190:193], v[138:141]
	v_mfma_f32_16x16x32_bf16 v[154:157], v[174:177], v[206:209], v[154:157]
	ds_read_b128 v[174:177], v237 offset:45056
	s_waitcnt lgkmcnt(2)
	v_mfma_f32_16x16x32_bf16 v[142:145], v[162:165], v[178:181], v[246:249]
	v_mfma_f32_16x16x32_bf16 v[158:161], v[162:165], v[194:197], v[250:253]
	ds_read_b128 v[162:165], v242 offset:32768
	v_mfma_f32_16x16x32_bf16 v[142:145], v[166:169], v[182:185], v[142:145]
	v_mfma_f32_16x16x32_bf16 v[158:161], v[166:169], v[198:201], v[158:161]
	ds_read_b128 v[166:169], v243 offset:32768
	s_waitcnt lgkmcnt(2)
	v_mfma_f32_16x16x32_bf16 v[142:145], v[170:173], v[186:189], v[142:145]
	v_mfma_f32_16x16x32_bf16 v[158:161], v[170:173], v[202:205], v[158:161]
	ds_read_b128 v[170:173], v242 offset:34816
	v_mfma_f32_16x16x32_bf16 v[142:145], v[174:177], v[190:193], v[142:145]
	v_mfma_f32_16x16x32_bf16 v[158:161], v[174:177], v[206:209], v[158:161]
	ds_read_b128 v[174:177], v243 offset:34816

.Lat_end_b:
.Lat_done:
	s_waitcnt vmcnt(0) lgkmcnt(0)
	v_lshl_add_u32 v250, v211, 4, s97
	ds_read_b128 v[130:133], v250
	ds_read_b128 v[134:137], v250 offset:1024
	ds_read_b128 v[138:141], v250 offset:2048
	ds_read_b128 v[142:145], v250 offset:3072
	ds_read_b128 v[146:149], v250 offset:4096
	ds_read_b128 v[150:153], v250 offset:5120
	ds_read_b128 v[154:157], v250 offset:6144
	ds_read_b128 v[158:161], v250 offset:7168
	s_waitcnt lgkmcnt(0)
	s_barrier
	s_mov_b32 m0, s92
	s_nop 1
	v_permlane16_swap_b32_e32 v232, v244
	v_add_f32_e32 v232, v232, v244
	v_mov_b32_e32 v244, v232
	s_nop 1
	v_permlane32_swap_b32_e32 v232, v244
	v_add_f32_e32 v232, v232, v244
	v_mov_b32_e32 v244, v232
	s_nop 1
	v_permlane16_swap_b32_e32 v232, v244
	s_nop 0
	v_div_scale_f32 v162, s[6:7], v232, v232, 1.0
	v_rcp_f32_e32 v163, v162
	v_div_scale_f32 v164, vcc, 1.0, v232, 1.0
	v_fma_f32 v165, -v162, v163, 1.0
	v_fmac_f32_e32 v163, v165, v163
	v_mul_f32_e32 v165, v164, v163
	v_fma_f32 v166, -v162, v165, v164
	v_fmac_f32_e32 v165, v166, v163
	v_fma_f32 v162, -v162, v165, v164
	v_div_fmas_f32 v162, v162, v163, v165
	v_div_fixup_f32 v232, v162, v232, 1.0
	v_div_scale_f32 v167, s[6:7], v244, v244, 1.0
	v_rcp_f32_e32 v168, v167
	v_div_scale_f32 v169, vcc, 1.0, v244, 1.0
	v_fma_f32 v170, -v167, v168, 1.0
	v_fmac_f32_e32 v168, v170, v168
	v_mul_f32_e32 v170, v169, v168
	v_fma_f32 v171, -v167, v170, v169
	v_fmac_f32_e32 v170, v171, v168
	v_fma_f32 v167, -v167, v170, v169
	v_div_fmas_f32 v167, v167, v168, v170
	v_div_fixup_f32 v244, v167, v244, 1.0
	s_lshl_b64 s[4:5], s[82:83], 1
	v_mul_f32_e32 v114, v114, v232
	v_mul_f32_e32 v115, v115, v232
	v_mul_f32_e32 v116, v116, v232
	v_mul_f32_e32 v117, v117, v232
	v_mul_f32_e32 v118, v118, v232
	v_mul_f32_e32 v119, v119, v232
	v_mul_f32_e32 v120, v120, v232
	v_mul_f32_e32 v121, v121, v232
	v_mul_f32_e32 v98, v98, v232
	v_mul_f32_e32 v99, v99, v232
	v_mul_f32_e32 v100, v100, v232
	v_mul_f32_e32 v101, v101, v232
	v_mul_f32_e32 v102, v102, v232
	v_mul_f32_e32 v103, v103, v232
	v_mul_f32_e32 v104, v104, v232
	v_mul_f32_e32 v105, v105, v232
	v_mul_f32_e32 v82, v82, v232
	v_mul_f32_e32 v83, v83, v232
	v_mul_f32_e32 v84, v84, v232
	v_mul_f32_e32 v85, v85, v232
	v_mul_f32_e32 v86, v86, v232
	v_mul_f32_e32 v87, v87, v232
	v_mul_f32_e32 v88, v88, v232
	v_mul_f32_e32 v89, v89, v232
	v_mul_f32_e32 v66, v66, v232
	v_mul_f32_e32 v67, v67, v232
	v_mul_f32_e32 v68, v68, v232
	v_mul_f32_e32 v69, v69, v232
	v_mul_f32_e32 v70, v70, v232
	v_mul_f32_e32 v71, v71, v232
	v_mul_f32_e32 v72, v72, v232
	v_mul_f32_e32 v73, v73, v232
	v_mul_f32_e32 v50, v50, v232
	v_mul_f32_e32 v51, v51, v232
	v_mul_f32_e32 v52, v52, v232
	v_mul_f32_e32 v53, v53, v232
	v_mul_f32_e32 v54, v54, v232
	v_mul_f32_e32 v55, v55, v232
	v_mul_f32_e32 v56, v56, v232
	v_mul_f32_e32 v57, v57, v232
	v_mul_f32_e32 v34, v34, v232
	v_mul_f32_e32 v35, v35, v232
	v_mul_f32_e32 v36, v36, v232
	v_mul_f32_e32 v37, v37, v232
	v_mul_f32_e32 v38, v38, v232
	v_mul_f32_e32 v39, v39, v232
	v_mul_f32_e32 v40, v40, v232
	v_mul_f32_e32 v41, v41, v232
	v_mul_f32_e32 v18, v18, v232
	v_mul_f32_e32 v19, v19, v232
	v_mul_f32_e32 v20, v20, v232
	v_mul_f32_e32 v21, v21, v232
	v_mul_f32_e32 v22, v22, v232
	v_mul_f32_e32 v23, v23, v232
	v_mul_f32_e32 v24, v24, v232
	v_mul_f32_e32 v25, v25, v232
	v_mul_f32_e32 v2, v2, v232
	v_mul_f32_e32 v3, v3, v232
	v_mul_f32_e32 v4, v4, v232
	v_mul_f32_e32 v5, v5, v232
	v_mul_f32_e32 v6, v6, v232
	v_mul_f32_e32 v7, v7, v232
	v_mul_f32_e32 v8, v8, v232
	v_mul_f32_e32 v9, v9, v232
	v_mul_f32_e32 v122, v122, v244
	v_mul_f32_e32 v123, v123, v244
	v_mul_f32_e32 v124, v124, v244
	v_mul_f32_e32 v125, v125, v244
	v_mul_f32_e32 v126, v126, v244
	v_mul_f32_e32 v127, v127, v244
	v_mul_f32_e32 v128, v128, v244
	v_mul_f32_e32 v129, v129, v244
	v_mul_f32_e32 v106, v106, v244
	v_mul_f32_e32 v107, v107, v244
	v_mul_f32_e32 v108, v108, v244
	v_mul_f32_e32 v109, v109, v244
	v_mul_f32_e32 v110, v110, v244
	v_mul_f32_e32 v111, v111, v244
	v_mul_f32_e32 v112, v112, v244
	v_mul_f32_e32 v113, v113, v244
	v_mul_f32_e32 v90, v90, v244
	v_mul_f32_e32 v91, v91, v244
	v_mul_f32_e32 v92, v92, v244
	v_mul_f32_e32 v93, v93, v244
	v_mul_f32_e32 v94, v94, v244
	v_mul_f32_e32 v95, v95, v244
	v_mul_f32_e32 v96, v96, v244
	v_mul_f32_e32 v97, v97, v244
	v_mul_f32_e32 v74, v74, v244
	v_mul_f32_e32 v75, v75, v244
	v_mul_f32_e32 v76, v76, v244
	v_mul_f32_e32 v77, v77, v244
	v_mul_f32_e32 v78, v78, v244
	v_mul_f32_e32 v79, v79, v244
	v_mul_f32_e32 v80, v80, v244
	v_mul_f32_e32 v81, v81, v244
	v_mul_f32_e32 v58, v58, v244
	v_mul_f32_e32 v59, v59, v244
	v_mul_f32_e32 v60, v60, v244
	v_mul_f32_e32 v61, v61, v244
	v_mul_f32_e32 v62, v62, v244
	v_mul_f32_e32 v63, v63, v244
	v_mul_f32_e32 v64, v64, v244
	v_mul_f32_e32 v65, v65, v244
	v_mul_f32_e32 v42, v42, v244
	v_mul_f32_e32 v43, v43, v244
	v_mul_f32_e32 v44, v44, v244
	v_mul_f32_e32 v45, v45, v244
	v_mul_f32_e32 v46, v46, v244
	v_mul_f32_e32 v47, v47, v244
	v_mul_f32_e32 v48, v48, v244
	v_mul_f32_e32 v49, v49, v244
	v_mul_f32_e32 v26, v26, v244
	v_mul_f32_e32 v27, v27, v244
	v_mul_f32_e32 v28, v28, v244
	v_mul_f32_e32 v29, v29, v244
	v_mul_f32_e32 v30, v30, v244
	v_mul_f32_e32 v31, v31, v244
	v_mul_f32_e32 v32, v32, v244
	v_mul_f32_e32 v33, v33, v244
	v_mul_f32_e32 v10, v10, v244
	v_mul_f32_e32 v11, v11, v244
	v_mul_f32_e32 v12, v12, v244
	v_mul_f32_e32 v13, v13, v244
	v_mul_f32_e32 v14, v14, v244
	v_mul_f32_e32 v15, v15, v244
	v_mul_f32_e32 v16, v16, v244
	v_mul_f32_e32 v17, v17, v244
	s_cmp_lg_u64 s[0:1], 0
	s_cbranch_scc1 .Lat_ep_k
	v_mul_f32_e32 v114, v114, v210
	v_mul_f32_e32 v115, v115, v210
	v_mul_f32_e32 v116, v116, v210
	v_mul_f32_e32 v117, v117, v210
	v_mul_f32_e32 v118, v118, v210
	v_mul_f32_e32 v119, v119, v210
	v_mul_f32_e32 v120, v120, v210
	v_mul_f32_e32 v121, v121, v210
	v_mul_f32_e32 v98, v98, v210
	v_mul_f32_e32 v99, v99, v210
	v_mul_f32_e32 v100, v100, v210
	v_mul_f32_e32 v101, v101, v210
	v_mul_f32_e32 v102, v102, v210
	v_mul_f32_e32 v103, v103, v210
	v_mul_f32_e32 v104, v104, v210
	v_mul_f32_e32 v105, v105, v210
	v_mul_f32_e32 v82, v82, v210
	v_mul_f32_e32 v83, v83, v210
	v_mul_f32_e32 v84, v84, v210
	v_mul_f32_e32 v85, v85, v210
	v_mul_f32_e32 v86, v86, v210
	v_mul_f32_e32 v87, v87, v210
	v_mul_f32_e32 v88, v88, v210
	v_mul_f32_e32 v89, v89, v210
	v_mul_f32_e32 v66, v66, v210
	v_mul_f32_e32 v67, v67, v210
	v_mul_f32_e32 v68, v68, v210
	v_mul_f32_e32 v69, v69, v210
	v_mul_f32_e32 v70, v70, v210
	v_mul_f32_e32 v71, v71, v210
	v_mul_f32_e32 v72, v72, v210
	v_mul_f32_e32 v73, v73, v210
	v_mul_f32_e32 v50, v50, v210
	v_mul_f32_e32 v51, v51, v210
	v_mul_f32_e32 v52, v52, v210
	v_mul_f32_e32 v53, v53, v210
	v_mul_f32_e32 v54, v54, v210
	v_mul_f32_e32 v55, v55, v210
	v_mul_f32_e32 v56, v56, v210
	v_mul_f32_e32 v57, v57, v210
	v_mul_f32_e32 v34, v34, v210
	v_mul_f32_e32 v35, v35, v210
	v_mul_f32_e32 v36, v36, v210
	v_mul_f32_e32 v37, v37, v210
	v_mul_f32_e32 v38, v38, v210
	v_mul_f32_e32 v39, v39, v210
	v_mul_f32_e32 v40, v40, v210
	v_mul_f32_e32 v41, v41, v210
	v_mul_f32_e32 v18, v18, v210
	v_mul_f32_e32 v19, v19, v210
	v_mul_f32_e32 v20, v20, v210
	v_mul_f32_e32 v21, v21, v210
	v_mul_f32_e32 v22, v22, v210
	v_mul_f32_e32 v23, v23, v210
	v_mul_f32_e32 v24, v24, v210
	v_mul_f32_e32 v25, v25, v210
	v_mul_f32_e32 v2, v2, v210
	v_mul_f32_e32 v3, v3, v210
	v_mul_f32_e32 v4, v4, v210
	v_mul_f32_e32 v5, v5, v210
	v_mul_f32_e32 v6, v6, v210
	v_mul_f32_e32 v7, v7, v210
	v_mul_f32_e32 v8, v8, v210
	v_mul_f32_e32 v9, v9, v210
	v_mul_f32_e32 v122, v122, v210
	v_mul_f32_e32 v123, v123, v210
	v_mul_f32_e32 v124, v124, v210
	v_mul_f32_e32 v125, v125, v210
	v_mul_f32_e32 v126, v126, v210
	v_mul_f32_e32 v127, v127, v210
	v_mul_f32_e32 v128, v128, v210
	v_mul_f32_e32 v129, v129, v210
	v_mul_f32_e32 v106, v106, v210
	v_mul_f32_e32 v107, v107, v210
	v_mul_f32_e32 v108, v108, v210
	v_mul_f32_e32 v109, v109, v210
	v_mul_f32_e32 v110, v110, v210
	v_mul_f32_e32 v111, v111, v210
	v_mul_f32_e32 v112, v112, v210
	v_mul_f32_e32 v113, v113, v210
	v_mul_f32_e32 v90, v90, v210
	v_mul_f32_e32 v91, v91, v210
	v_mul_f32_e32 v92, v92, v210
	v_mul_f32_e32 v93, v93, v210
	v_mul_f32_e32 v94, v94, v210
	v_mul_f32_e32 v95, v95, v210
	v_mul_f32_e32 v96, v96, v210
	v_mul_f32_e32 v97, v97, v210
	v_mul_f32_e32 v74, v74, v210
	v_mul_f32_e32 v75, v75, v210
	v_mul_f32_e32 v76, v76, v210
	v_mul_f32_e32 v77, v77, v210
	v_mul_f32_e32 v78, v78, v210
	v_mul_f32_e32 v79, v79, v210
	v_mul_f32_e32 v80, v80, v210
	v_mul_f32_e32 v81, v81, v210
	v_mul_f32_e32 v58, v58, v210
	v_mul_f32_e32 v59, v59, v210
	v_mul_f32_e32 v60, v60, v210
	v_mul_f32_e32 v61, v61, v210
	v_mul_f32_e32 v62, v62, v210
	v_mul_f32_e32 v63, v63, v210
	v_mul_f32_e32 v64, v64, v210
	v_mul_f32_e32 v65, v65, v210
	v_mul_f32_e32 v42, v42, v210
	v_mul_f32_e32 v43, v43, v210
	v_mul_f32_e32 v44, v44, v210
	v_mul_f32_e32 v45, v45, v210
	v_mul_f32_e32 v46, v46, v210
	v_mul_f32_e32 v47, v47, v210
	v_mul_f32_e32 v48, v48, v210
	v_mul_f32_e32 v49, v49, v210
	v_mul_f32_e32 v26, v26, v210
	v_mul_f32_e32 v27, v27, v210
	v_mul_f32_e32 v28, v28, v210
	v_mul_f32_e32 v29, v29, v210
	v_mul_f32_e32 v30, v30, v210
	v_mul_f32_e32 v31, v31, v210
	v_mul_f32_e32 v32, v32, v210
	v_mul_f32_e32 v33, v33, v210
	v_mul_f32_e32 v10, v10, v210
	v_mul_f32_e32 v11, v11, v210
	v_mul_f32_e32 v12, v12, v210
	v_mul_f32_e32 v13, v13, v210
	v_mul_f32_e32 v14, v14, v210
	v_mul_f32_e32 v15, v15, v210
	v_mul_f32_e32 v16, v16, v210
	v_mul_f32_e32 v17, v17, v210
	v_lshl_add_u32 v250, v211, 4, s95
	ds_write_b128 v250, v[114:117]
	ds_write_b128 v250, v[118:121] offset:1024
	ds_write_b128 v250, v[98:101] offset:2048
	ds_write_b128 v250, v[102:105] offset:3072
	ds_write_b128 v250, v[82:85] offset:4096
	ds_write_b128 v250, v[86:89] offset:5120
	ds_write_b128 v250, v[66:69] offset:6144
	ds_write_b128 v250, v[70:73] offset:7168
	ds_write_b128 v250, v[50:53] offset:8192
	ds_write_b128 v250, v[54:57] offset:9216
	ds_write_b128 v250, v[34:37] offset:10240
	ds_write_b128 v250, v[38:41] offset:11264
	ds_write_b128 v250, v[18:21] offset:12288
	ds_write_b128 v250, v[22:25] offset:13312
	ds_write_b128 v250, v[2:5] offset:14336
	ds_write_b128 v250, v[6:9] offset:15360
	ds_write_b128 v250, v[122:125] offset:16384
	ds_write_b128 v250, v[126:129] offset:17408
	ds_write_b128 v250, v[106:109] offset:18432
	ds_write_b128 v250, v[110:113] offset:19456
	ds_write_b128 v250, v[90:93] offset:20480
	ds_write_b128 v250, v[94:97] offset:21504
	ds_write_b128 v250, v[74:77] offset:22528
	ds_write_b128 v250, v[78:81] offset:23552
	ds_write_b128 v250, v[58:61] offset:24576
	ds_write_b128 v250, v[62:65] offset:25600
	ds_write_b128 v250, v[42:45] offset:26624
	ds_write_b128 v250, v[46:49] offset:27648
	ds_write_b128 v250, v[26:29] offset:28672
	ds_write_b128 v250, v[30:33] offset:29696
	ds_write_b128 v250, v[10:13] offset:30720
	ds_write_b128 v250, v[14:17] offset:31744
	s_waitcnt lgkmcnt(0)
	s_barrier
	s_branch .Lat_ep_fin
